# barrier: every workgroup writes back L2 on arrival (leader write-back removed) + early L1 invalidate
# baseline (speedup 1.0000x reference)
; __device__ __forceinline__ void xcd_barrier(const XcdBarrier& b) {
;     asm volatile("s_waitcnt vmcnt(0)" ::: "memory");
;     __syncthreads();
;     if (threadIdx.x == 0) {
;         unsigned* bar = b.bar;
;         __builtin_amdgcn_s_waitcnt(0);
;         unsigned nloc = b.st[0], nx = b.st[1];
;         if (nloc == 0u) { xcd_barrier_complete(bar, b.x, nloc, nx); b.st[0] = nloc; b.st[1] = nx; }
; __global__ void __launch_bounds__(NTHREADS, 2) mk_fwd(Params P_arg) {
;     ...
;         if (did && ph + 1 < P_arg.ph_hi) { if (ph == 99) grid.sync(); else xcd_barrier(xbar); if (PROBE_DUP == 5) xcd_barrier(xbar); }
.LBB0_495:
	v_readlane_b32 s4, v247, 40
	s_add_i32 s50, s4, 1
	s_cmp_ge_i32 s50, s51
	s_cselect_b64 s[0:1], -1, 0
	s_cmp_lt_i32 s50, s51
	s_cselect_b64 s[2:3], -1, 0
	s_and_b64 s[2:3], s[16:17], s[2:3]
	s_andn2_b64 vcc, exec, s[2:3]
	s_cbranch_vccnz .LBB0_10
	s_cmpk_lg_i32 s4, 0x63
	s_mov_b64 s[4:5], -1
	s_cbranch_scc0 .LBB0_550
	s_waitcnt vmcnt(0)
	s_waitcnt vmcnt(0) lgkmcnt(0)
	s_barrier
	s_mov_b64 s[4:5], exec
	v_readlane_b32 s2, v248, 4
	v_readlane_b32 s3, v248, 5
	s_and_b64 s[2:3], s[4:5], s[2:3]
	s_mov_b64 exec, s[2:3]
	s_cbranch_execz .LBB0_549
	v_readlane_b32 s2, v247, 27
	buffer_wbl2 sc1
	s_waitcnt vmcnt(0) expcnt(0) lgkmcnt(0)
	buffer_inv sc1
	s_nop 0
	v_mov_b32_e32 v0, s2
	ds_read_b32 v3, v0
	v_readlane_b32 s2, v247, 28
	s_waitcnt lgkmcnt(0)
	v_cmp_ne_u32_e32 vcc, 0, v3
	v_mov_b32_e32 v0, s2
	ds_read_b32 v2, v0
	s_cbranch_vccnz .LBB0_513
	s_mov_b32 s2, 1
	s_branch .LBB0_501

; __device__ __forceinline__ unsigned xb_add(unsigned* p, unsigned v) { return __hip_atomic_fetch_add(p, v, __ATOMIC_RELAXED, __HIP_MEMORY_SCOPE_AGENT); }
; __device__ __forceinline__ void xcd_barrier(const XcdBarrier& b) {
;     ...
;         const unsigned old = xb_add(&bar[XB_XSUB(b.x)], 1u);
;         const unsigned gen = old / nloc;
;         if (old + 1u == (gen + 1u) * nloc) {
;             __builtin_amdgcn_fence(__ATOMIC_RELEASE, "agent");
;             asm volatile("s_waitcnt vmcnt(0)" ::: "memory");
;             const unsigned og = xb_add(&bar[XB_TOP], 1u);
.LBB0_529:
	s_andn2_saveexec_b64 s[2:3], s[6:7]
	s_cbranch_execz .LBB0_549
	s_mov_b64 s[6:7], exec
	s_nop 0
	s_waitcnt lgkmcnt(0)
	s_waitcnt vmcnt(0)
	v_mbcnt_lo_u32_b32 v0, s6, 0
	v_mbcnt_hi_u32_b32 v0, s7, v0
	v_cmp_eq_u32_e32 vcc, 0, v0
	s_and_saveexec_b64 s[8:9], vcc
	s_cbranch_execz .LBB0_532
	s_bcnt1_i32_b64 s2, s[6:7]
	v_mov_b32_e32 v3, s2
	v_readlane_b32 s2, v247, 16
	v_readlane_b32 s3, v247, 17
	s_nop 4
	global_atomic_add v3, v1, v3, s[2:3] sc0
